# softmax: running max folded into QK accumulator init (per-lane -m block as MFMA SrcC), exps in place, no per-element subtraction; on top of ping-pong attention + lean DMA + P10 epilogue
# speedup vs baseline: 1.0394x; 1.0199x over previous
.LBB0_1264:
	s_lshl_b32 s87, s35, 2
	s_xor_b64 s[16:17], s[44:45], -1
	s_add_i32 s87, s87, 4
	s_ashr_i32 s89, s86, 6
	s_movk_i32 s35, 0x110
	s_cmp_lt_u32 s85, 26
	v_mad_u32_u24 v229, v227, s35, v214
	s_cselect_b64 s[50:51], -1, 0
	s_lshl_b32 s35, s85, 10
	s_cmp_lt_u32 s6, 26
	s_cselect_b64 s[54:55], -1, 0
	s_lshl_b32 s44, s6, 10
	s_cmp_lt_u32 s7, 26
	s_cselect_b64 s[58:59], -1, 0
	s_lshl_b32 s45, s7, 10
	s_cmp_lt_u32 s14, 26
	s_cselect_b64 s[6:7], -1, 0
	s_lshl_b32 s46, s14, 10
	s_cmp_lt_u32 s15, 26
	s_cselect_b64 s[66:67], -1, 0
	s_lshl_b32 s47, s15, 10
	s_cmp_lt_u32 s33, 26
	s_cselect_b64 s[14:15], -1, 0
	s_lshl_b32 s33, s33, 10
	s_add_i32 s88, s35, 0
	s_add_i32 s90, s44, 0
	s_add_i32 s91, s45, 0
	s_add_i32 s92, s46, 0
	s_add_i32 s93, s47, 0
	s_add_i32 s94, s33, 0
	s_and_b64 s[44:45], s[50:51], exec
	s_cselect_b32 s33, s73, s37
	s_cselect_b32 s35, s74, s38
	s_cmp_lt_i32 s85, 26
	s_cselect_b64 s[44:45], -1, 0
	s_and_b64 s[46:47], s[48:49], exec
	s_cselect_b32 s47, s9, s35
	s_cselect_b32 s46, s8, s33
	s_and_b64 s[50:51], s[50:51], exec
	s_cselect_b32 s33, 13, 7
	s_and_b64 s[48:49], s[48:49], exec
	s_cselect_b32 s95, 18, s33
	s_and_b64 s[48:49], s[54:55], exec
	s_cselect_b32 s33, s73, s37
	s_cselect_b32 s35, s74, s38
	s_cmp_lt_i32 s85, 18
	s_cselect_b64 s[48:49], -1, 0
	s_and_b64 s[50:51], exec, s[52:53]
	s_cselect_b32 s51, s9, s35
	s_cselect_b32 s50, s8, s33
	s_and_b64 s[54:55], s[54:55], exec
	s_cselect_b32 s33, 13, 7
	s_and_b64 s[52:53], exec, s[52:53]
	s_cselect_b32 s96, 18, s33
	s_and_b64 s[52:53], s[58:59], exec
	s_cselect_b32 s33, s73, s37
	s_cselect_b32 s35, s74, s38
	s_cmp_lt_i32 s85, 10
	s_cselect_b64 s[52:53], -1, 0
	s_and_b64 s[54:55], exec, s[56:57]
	s_cselect_b32 s55, s9, s35
	s_cselect_b32 s54, s8, s33
	s_and_b64 s[58:59], s[58:59], exec
	s_cselect_b32 s33, 13, 7
	s_and_b64 s[56:57], exec, s[56:57]
	s_cselect_b32 s97, 18, s33
	s_and_b64 s[56:57], s[6:7], exec
	s_cselect_b32 s33, s73, s37
	s_cselect_b32 s35, s74, s38
	s_cmp_lt_i32 s85, 2
	s_cselect_b64 s[56:57], -1, 0
	s_and_b64 s[58:59], exec, s[60:61]
	s_cselect_b32 s59, s9, s35
	s_cselect_b32 s58, s8, s33
	s_and_b64 s[6:7], s[6:7], exec
	v_add_u32_e32 v230, 0, v229
	s_cselect_b32 s33, 13, 7
	s_and_b64 s[6:7], exec, s[60:61]
	s_waitcnt vmcnt(0)
	s_waitcnt vmcnt(0) lgkmcnt(0)
	s_barrier
	ds_read_b128 v[112:115], v1
	ds_read_b128 v[116:119], v1 offset:32
	ds_read_b128 v[120:123], v1 offset:64
	ds_read_b128 v[124:127], v1 offset:96
	ds_read_b128 v[168:171], v230
	ds_read_b128 v[160:163], v230 offset:32
	ds_read_b128 v[164:167], v230 offset:64
	ds_read_b128 v[152:155], v230 offset:96
	ds_read_b128 v[156:159], v230 offset:128
	ds_read_b128 v[128:131], v230 offset:160
	ds_read_b128 v[132:135], v230 offset:192
	ds_read_b128 v[136:139], v230 offset:224
	s_cselect_b32 s6, 18, s33
	s_and_b64 s[60:61], s[66:67], exec
	v_lshlrev_b32_e32 v1, 7, v227
	s_cselect_b32 s7, s73, s37
	s_cselect_b32 s33, s74, s38
	s_cmp_lt_i32 s85, -6
	v_sub_u32_e32 v1, v229, v1
	s_cselect_b64 s[60:61], -1, 0
	s_and_b64 s[62:63], exec, s[64:65]
	v_add_u32_e32 v231, 0, v1
	s_cselect_b32 s63, s9, s33
	s_cselect_b32 s62, s8, s7
	s_and_b64 s[66:67], s[66:67], exec
	ds_read_b128 v[140:143], v231 offset:17408
	ds_read_b128 v[144:147], v231 offset:17440
	ds_read_b128 v[148:151], v231 offset:17472
	ds_read_b128 v[208:211], v231 offset:17504
	s_cselect_b32 s7, 13, 7
	s_and_b64 s[64:65], exec, s[64:65]
	s_cselect_b32 s7, 18, s7
	s_and_b64 s[64:65], s[14:15], exec
	s_cselect_b32 s33, s73, s37
	s_cselect_b32 s35, s74, s38
	s_cmp_lt_i32 s85, -14
	s_cselect_b64 s[64:65], -1, 0
	s_and_b64 s[66:67], exec, s[68:69]
	v_mul_u32_u24_e32 v2, 0x90, v227
	s_cselect_b32 s67, s9, s35
	s_cselect_b32 s66, s8, s33
	s_and_b64 s[14:15], s[14:15], exec
	v_mov_b32_e32 v14, v215
	v_mov_b32_e32 v15, v215
	v_lshlrev_b32_e32 v232, 2, v0
	s_cselect_b32 s33, 13, 7
	s_and_b64 s[14:15], exec, s[68:69]
	v_add_u32_e32 v233, v2, v214
	v_mov_b32_e32 v0, v215
	v_mov_b32_e32 v1, v215
	v_mov_b32_e32 v2, v215
	v_mov_b32_e32 v3, v215
	v_mov_b32_e32 v4, v215
	v_mov_b32_e32 v5, v215
	v_mov_b32_e32 v6, v215
	v_mov_b32_e32 v7, v215
	v_mov_b32_e32 v8, v215
	v_mov_b32_e32 v9, v215
	v_mov_b32_e32 v10, v215
	v_mov_b32_e32 v11, v215
	v_mov_b32_e32 v12, v215
	v_mov_b32_e32 v13, v215
	v_mov_b64_e32 v[30:31], v[14:15]
	v_mov_b64_e32 v[46:47], v[14:15]
	v_mov_b64_e32 v[62:63], v[14:15]
	s_cselect_b32 s33, 18, s33
	v_add_u32_e32 v234, 0, v233
	s_add_i32 s14, s34, 0x100
	s_mov_b32 s15, 0
	v_mov_b32_e32 v235, 0
	v_mov_b32_e32 v236, 0
	v_mov_b32_e32 v238, 0
	v_mov_b32_e32 v239, 0
	v_mov_b32_e32 v240, 0
	v_mov_b32_e32 v241, 0
	v_mov_b32_e32 v242, 0
	v_mov_b32_e32 v243, 0
	v_mov_b32_e32 v244, 0
	v_mov_b32_e32 v245, 0
	v_mov_b32_e32 v246, 0
	v_mov_b32_e32 v247, 0
	v_mov_b32_e32 v248, 0
	v_mov_b32_e32 v249, 0
	v_mov_b32_e32 v250, 0
	v_mov_b32_e32 v251, 0
	v_mov_b32_e32 v252, 0
	v_mov_b32_e32 v253, 0
	v_mov_b64_e32 v[28:29], v[12:13]
	v_mov_b64_e32 v[26:27], v[10:11]
	v_mov_b64_e32 v[24:25], v[8:9]
	v_mov_b64_e32 v[22:23], v[6:7]
	v_mov_b64_e32 v[20:21], v[4:5]
	v_mov_b64_e32 v[18:19], v[2:3]
	v_mov_b64_e32 v[16:17], v[0:1]
	v_mov_b64_e32 v[44:45], v[12:13]
	v_mov_b64_e32 v[42:43], v[10:11]
	v_mov_b64_e32 v[40:41], v[8:9]
	v_mov_b64_e32 v[38:39], v[6:7]
	v_mov_b64_e32 v[36:37], v[4:5]
	v_mov_b64_e32 v[34:35], v[2:3]
	v_mov_b64_e32 v[32:33], v[0:1]
	v_mov_b64_e32 v[60:61], v[12:13]
	v_mov_b64_e32 v[58:59], v[10:11]
	v_mov_b64_e32 v[56:57], v[8:9]
	v_mov_b64_e32 v[54:55], v[6:7]
	v_mov_b64_e32 v[52:53], v[4:5]
	v_mov_b64_e32 v[50:51], v[2:3]
	v_mov_b64_e32 v[48:49], v[0:1]
	s_mov_b32 s35, 0
	s_and_b32 s45, s85, 3
	s_lshl_b32 s44, s45, 10
	s_mov_b32 s52, s73
	s_mov_b32 s53, s74
	s_mov_b32 s54, s37
	s_mov_b32 s55, s38
	s_cmp_ge_u32 s85, 4
	s_cbranch_scc1 .Lxd_sy
	s_add_i32 s18, s45, 0
	s_lshl_b32 s18, s18, 10
	v_lshl_add_u32 v72, v219, 4, s18
	s_mov_b32 s19, 15790321
	v_mul_hi_u32 v73, v72, s19
	v_mul_u32_u24_e32 v74, 272, v73
	v_sub_u32_e32 v74, v72, v74
	v_min_u32_e32 v74, 240, v74
	v_lshlrev_b32_e32 v75, 12, v73
	v_add3_u32 v221, v75, v74, s84
	s_add_i32 s18, s45, 4
	s_lshl_b32 s18, s18, 10
	v_lshl_add_u32 v72, v219, 4, s18
	s_mov_b32 s19, 15790321
	v_mul_hi_u32 v73, v72, s19
	v_mul_u32_u24_e32 v74, 272, v73
	v_sub_u32_e32 v74, v72, v74
	v_min_u32_e32 v74, 240, v74
	v_lshlrev_b32_e32 v75, 12, v73
	v_add3_u32 v222, v75, v74, s84
	s_add_i32 s18, s45, 8
	s_lshl_b32 s18, s18, 10
	v_lshl_add_u32 v72, v219, 4, s18
	s_mov_b32 s19, 15790321
	v_mul_hi_u32 v73, v72, s19
	v_mul_u32_u24_e32 v74, 272, v73
	v_sub_u32_e32 v74, v72, v74
	v_min_u32_e32 v74, 240, v74
	v_lshlrev_b32_e32 v75, 12, v73
	v_add3_u32 v223, v75, v74, s84
	s_add_i32 s18, s45, 12
	s_lshl_b32 s18, s18, 10
	v_lshl_add_u32 v72, v219, 4, s18
	s_mov_b32 s19, 15790321
	v_mul_hi_u32 v73, v72, s19
	v_mul_u32_u24_e32 v74, 272, v73
	v_sub_u32_e32 v74, v72, v74
	v_min_u32_e32 v74, 240, v74
	v_lshlrev_b32_e32 v75, 12, v73
	v_add3_u32 v224, v75, v74, s84
	s_cmp_ge_u32 s45, 1
	s_cselect_b32 s18, -1, 16
	s_mov_b32 s24, 29826162
	s_mov_b32 s25, 15790321
	s_cselect_b32 s19, s24, s25
	s_mov_b32 s24, 144
	s_mov_b32 s25, 272
	s_cselect_b32 s20, s24, s25
	s_mov_b32 s24, 112
	s_mov_b32 s25, 240
	s_cselect_b32 s21, s24, s25
	s_cselect_b32 s22, 7, 12
	s_cselect_b32 s23, 0, s84
	s_add_i32 s18, s45, s18
	s_lshl_b32 s18, s18, 10
	v_lshl_add_u32 v72, v219, 4, s18
	v_mul_hi_u32 v73, v72, s19
	v_mul_lo_u32 v74, v73, s20
	v_sub_u32_e32 v74, v72, v74
	v_min_u32_e32 v74, s21, v74
	v_lshlrev_b32_e32 v75, s22, v73
	v_add3_u32 v225, v75, v74, s23
	s_add_i32 s18, s45, 3
	s_lshl_b32 s18, s18, 10
	v_lshl_add_u32 v72, v219, 4, s18
	s_mov_b32 s19, 29826162
	v_mul_hi_u32 v73, v72, s19
	v_mul_u32_u24_e32 v74, 144, v73
	v_sub_u32_e32 v74, v72, v74
	v_min_u32_e32 v74, 112, v74
	v_lshlrev_b32_e32 v75, 7, v73
	v_add_u32_e32 v226, v75, v74
	s_cmp_ge_u32 s45, 1
	s_cselect_b32 s95, 13, 18
	s_cselect_b32 s46, s73, s8
	s_cselect_b32 s47, s74, s9
	s_branch .Lxd_sdone

.LBB0_1278:
	s_cmp_le_i32 s35, s89
	s_cselect_b64 s[70:71], -1, 0
	s_cmp_gt_i32 s35, s89
	s_cbranch_scc1 .LBB0_1288
	s_and_b32 vcc_lo, s35, 1
	s_mul_i32 vcc_hi, vcc_lo, 0x4800
	v_add_u32_e32 v237, vcc_hi, v234
	v_add_u32_e32 v217, 0xd000, v237
	s_mulk_i32 vcc_lo, 0x6800
	s_add_i32 vcc_lo, vcc_lo, 0
	s_setprio 1
	s_waitcnt lgkmcnt(0)
	v_mfma_f32_32x32x16_bf16 v[64:79], v[168:171], v[80:83], v[238:253]
	ds_read_b128 v[180:183], v237 offset:53248
	ds_read_b128 v[176:179], v237 offset:53280
	v_add_u32_e32 v172, vcc_lo, v229
	v_add_u32_e32 v218, vcc_lo, v233
	v_mfma_f32_32x32x16_bf16 v[64:79], v[160:163], v[84:87], v[64:79]
	ds_read_b128 v[196:199], v237 offset:57856
	ds_read_b128 v[188:191], v237 offset:62464
	v_mfma_f32_32x32x16_bf16 v[64:79], v[164:167], v[88:91], v[64:79]
	ds_read_b128 v[200:203], v217 offset:13824
	ds_read_b128 v[184:187], v217 offset:13856
	v_mfma_f32_32x32x16_bf16 v[64:79], v[152:155], v[92:95], v[64:79]
	ds_read_b128 v[204:207], v237 offset:57888
	ds_read_b128 v[192:195], v237 offset:62496
	v_mfma_f32_32x32x16_bf16 v[64:79], v[156:159], v[96:99], v[64:79]
	ds_read_b128 v[168:171], v172 offset:8704
	ds_read_b128 v[160:163], v172 offset:8736
	v_mfma_f32_32x32x16_bf16 v[64:79], v[128:131], v[100:103], v[64:79]
	ds_read_b128 v[164:167], v172 offset:8768
	ds_read_b128 v[152:155], v172 offset:8800
	v_mfma_f32_32x32x16_bf16 v[64:79], v[132:135], v[104:107], v[64:79]
	ds_read_b128 v[156:159], v172 offset:8832
	ds_read_b128 v[128:131], v172 offset:8864
	v_mfma_f32_32x32x16_bf16 v[64:79], v[136:139], v[108:111], v[64:79]
	ds_read_b128 v[132:135], v172 offset:8896
	ds_read_b128 v[136:139], v172 offset:8928
	v_mfma_f32_32x32x16_bf16 v[64:79], v[140:143], v[112:115], v[64:79]
	ds_read_b128 v[140:143], v218 offset:22016
	ds_read_b128 v[172:175], v218 offset:22112
	v_mfma_f32_32x32x16_bf16 v[64:79], v[144:147], v[116:119], v[64:79]
	ds_read_b128 v[144:147], v218 offset:22048
	v_mfma_f32_32x32x16_bf16 v[64:79], v[148:151], v[120:123], v[64:79]
	ds_read_b128 v[148:151], v218 offset:22080
	v_mfma_f32_32x32x16_bf16 v[64:79], v[208:211], v[124:127], v[64:79]
	s_setprio 0
	s_barrier
	s_and_b64 vcc, exec, s[68:69]
	s_cbranch_vccnz .Ldmq_end
	s_cmp_ge_u32 s85, 4
	s_cbranch_scc1 .Lxdq_y
	s_and_b32 s99, s34, 1
	s_mul_i32 s98, s99, 0x4800
	s_addk_i32 s98, 0x6800
	s_mulk_i32 s99, 0x6800
	s_add_i32 s99, s99, s44
	s_add_i32 s98, s98, s44
	s_lshl_b32 s94, s34, 18
	s_lshl_b32 s90, s34, 13
	s_lshl_b32 s91, s34, 7
	s_add_i32 m0, s99, 0x0
	v_add_u32_e32 v255, s94, v221
	global_load_lds_dwordx4 v255, s[8:9]
	s_add_i32 m0, s99, 0x1000
	v_add_u32_e32 v255, s94, v222
	global_load_lds_dwordx4 v255, s[8:9]
	s_add_i32 m0, s99, 0x2000
	v_add_u32_e32 v255, s94, v223
	global_load_lds_dwordx4 v255, s[8:9]
	s_add_i32 m0, s99, 0x3000
	v_add_u32_e32 v255, s94, v224
	global_load_lds_dwordx4 v255, s[8:9]
	s_lshl_b32 s92, s34, s95
	s_add_i32 m0, s99, 0x4000
	v_add_u32_e32 v255, s92, v225
	global_load_lds_dwordx4 v255, s[46:47]
	s_add_i32 m0, s99, 0x5000
	v_add_u32_e32 v255, s90, v226
	global_load_lds_dwordx4 v255, s[52:53]
	s_branch .Ldmq_end

.LBB0_1281:
	s_nop 7
	v_max_f32_e32 v211, v64, v65
	v_max3_f32 v211, v211, v66, v67
	v_max3_f32 v211, v211, v68, v69
	v_max3_f32 v211, v211, v70, v71
	v_max3_f32 v211, v211, v72, v73
	v_max3_f32 v211, v211, v74, v75
	v_max3_f32 v211, v211, v76, v77
	v_max3_f32 v211, v211, v78, v79
	v_mov_b32_e32 v208, v211
	s_nop 1
	v_permlane32_swap_b32_e32 v211, v208
	v_max_f32_e32 v211, v211, v208
	s_cmp_eq_u32 s35, 0
	s_cbranch_scc1 .Lci0_first
	v_cmp_lt_f32_e32 vcc, 0x41000000, v211
	s_cbranch_vccz .LBB0_1283
	v_max_f32_e32 v211, 0, v211
	v_exp_f32_e64 v208, -v211
	v_add_f32_e32 v236, v236, v211
	s_nop 0
	v_pk_mul_f32 v[62:63], v[62:63], v[208:209] op_sel_hi:[1,0]
	v_pk_mul_f32 v[60:61], v[60:61], v[208:209] op_sel_hi:[1,0]
	v_pk_mul_f32 v[58:59], v[58:59], v[208:209] op_sel_hi:[1,0]
	v_pk_mul_f32 v[56:57], v[56:57], v[208:209] op_sel_hi:[1,0]
	v_pk_mul_f32 v[54:55], v[54:55], v[208:209] op_sel_hi:[1,0]
	v_pk_mul_f32 v[52:53], v[52:53], v[208:209] op_sel_hi:[1,0]
	v_pk_mul_f32 v[50:51], v[50:51], v[208:209] op_sel_hi:[1,0]
	v_pk_mul_f32 v[48:49], v[48:49], v[208:209] op_sel_hi:[1,0]
	v_pk_mul_f32 v[46:47], v[46:47], v[208:209] op_sel_hi:[1,0]
	v_pk_mul_f32 v[44:45], v[44:45], v[208:209] op_sel_hi:[1,0]
	v_pk_mul_f32 v[42:43], v[42:43], v[208:209] op_sel_hi:[1,0]
	v_pk_mul_f32 v[40:41], v[40:41], v[208:209] op_sel_hi:[1,0]
	v_pk_mul_f32 v[38:39], v[38:39], v[208:209] op_sel_hi:[1,0]
	v_pk_mul_f32 v[36:37], v[36:37], v[208:209] op_sel_hi:[1,0]
	v_pk_mul_f32 v[34:35], v[34:35], v[208:209] op_sel_hi:[1,0]
	v_pk_mul_f32 v[32:33], v[32:33], v[208:209] op_sel_hi:[1,0]
	v_pk_mul_f32 v[30:31], v[30:31], v[208:209] op_sel_hi:[1,0]
	v_pk_mul_f32 v[28:29], v[28:29], v[208:209] op_sel_hi:[1,0]
	v_pk_mul_f32 v[26:27], v[26:27], v[208:209] op_sel_hi:[1,0]
	v_pk_mul_f32 v[24:25], v[24:25], v[208:209] op_sel_hi:[1,0]
	v_pk_mul_f32 v[22:23], v[22:23], v[208:209] op_sel_hi:[1,0]
	v_pk_mul_f32 v[20:21], v[20:21], v[208:209] op_sel_hi:[1,0]
	v_pk_mul_f32 v[18:19], v[18:19], v[208:209] op_sel_hi:[1,0]
	v_pk_mul_f32 v[16:17], v[16:17], v[208:209] op_sel_hi:[1,0]
	v_pk_mul_f32 v[14:15], v[14:15], v[208:209] op_sel_hi:[1,0]
	v_pk_mul_f32 v[12:13], v[12:13], v[208:209] op_sel_hi:[1,0]
	v_pk_mul_f32 v[10:11], v[10:11], v[208:209] op_sel_hi:[1,0]
	v_pk_mul_f32 v[8:9], v[8:9], v[208:209] op_sel_hi:[1,0]
	v_pk_mul_f32 v[6:7], v[6:7], v[208:209] op_sel_hi:[1,0]
	v_pk_mul_f32 v[4:5], v[4:5], v[208:209] op_sel_hi:[1,0]
	v_pk_mul_f32 v[2:3], v[2:3], v[208:209] op_sel_hi:[1,0]
	v_pk_mul_f32 v[0:1], v[0:1], v[208:209] op_sel_hi:[1,0]
	v_mul_f32_e32 v235, v235, v208
	s_branch .Lci0_tail
.Lci0_first:
	v_add_f32_e32 v236, v236, v211
.Lci0_tail:
	v_sub_f32_e32 v64, v64, v211
	v_sub_f32_e32 v65, v65, v211
	v_sub_f32_e32 v66, v66, v211
	v_sub_f32_e32 v67, v67, v211
	v_sub_f32_e32 v68, v68, v211
	v_sub_f32_e32 v69, v69, v211
	v_sub_f32_e32 v70, v70, v211
	v_sub_f32_e32 v71, v71, v211
	v_sub_f32_e32 v72, v72, v211
	v_sub_f32_e32 v73, v73, v211
	v_sub_f32_e32 v74, v74, v211
	v_sub_f32_e32 v75, v75, v211
	v_sub_f32_e32 v76, v76, v211
	v_sub_f32_e32 v77, v77, v211
	v_sub_f32_e32 v78, v78, v211
	v_sub_f32_e32 v79, v79, v211
	v_sub_f32_e32 v238, v238, v211
	v_sub_f32_e32 v239, v239, v211
	v_sub_f32_e32 v240, v240, v211
	v_sub_f32_e32 v241, v241, v211
	v_sub_f32_e32 v242, v242, v211
	v_sub_f32_e32 v243, v243, v211
	v_sub_f32_e32 v244, v244, v211
	v_sub_f32_e32 v245, v245, v211
	v_sub_f32_e32 v246, v246, v211
	v_sub_f32_e32 v247, v247, v211
	v_sub_f32_e32 v248, v248, v211
	v_sub_f32_e32 v249, v249, v211
	v_sub_f32_e32 v250, v250, v211
	v_sub_f32_e32 v251, v251, v211
	v_sub_f32_e32 v252, v252, v211
	v_sub_f32_e32 v253, v253, v211
.LBB0_1283:
	v_exp_f32_e32 v64, v64
	v_exp_f32_e32 v65, v65
	v_exp_f32_e32 v66, v66
	v_exp_f32_e32 v67, v67
	v_exp_f32_e32 v68, v68
	v_add_f32_e32 v208, v64, v65
	v_exp_f32_e32 v69, v69
	v_exp_f32_e32 v70, v70
	v_add_f32_e32 v208, v66, v208
	v_exp_f32_e32 v71, v71
	v_add_f32_e32 v208, v67, v208
	v_exp_f32_e32 v72, v72
	v_add_f32_e32 v208, v68, v208
	v_exp_f32_e32 v73, v73
	v_add_f32_e32 v208, v69, v208
	v_exp_f32_e32 v74, v74
	v_add_f32_e32 v208, v70, v208
	v_exp_f32_e32 v75, v75
	v_add_f32_e32 v208, v71, v208
	v_exp_f32_e32 v76, v76
	v_add_f32_e32 v208, v72, v208
	v_exp_f32_e32 v77, v77
	v_add_f32_e32 v208, v73, v208
	v_exp_f32_e32 v78, v78
	v_add_f32_e32 v208, v74, v208
	v_exp_f32_e32 v79, v79
	v_add_f32_e32 v208, v75, v208
	v_add_f32_e32 v208, v76, v208
	v_add_f32_e32 v208, v77, v208
	v_add_f32_e32 v208, v78, v208
	v_add_f32_e32 v208, v79, v208
	v_add_f32_e32 v235, v235, v208
	v_cvt_pk_bf16_f32 v64, v64, v65
	v_cvt_pk_bf16_f32 v65, v66, v67
	v_cvt_pk_bf16_f32 v66, v68, v69
	v_cvt_pk_bf16_f32 v67, v70, v71
	v_cvt_pk_bf16_f32 v68, v72, v73
	v_cvt_pk_bf16_f32 v69, v74, v75
	v_cvt_pk_bf16_f32 v70, v76, v77
	v_cvt_pk_bf16_f32 v71, v78, v79
	s_barrier
	s_setprio 1
	s_waitcnt lgkmcnt(0)
	v_mfma_f32_32x32x16_bf16 v[48:63], v[180:183], v[64:67], v[48:63]
	v_mfma_f32_32x32x16_bf16 v[32:47], v[196:199], v[64:67], v[32:47]
	v_mfma_f32_32x32x16_bf16 v[16:31], v[188:191], v[64:67], v[16:31]
	v_mfma_f32_32x32x16_bf16 v[0:15], v[200:203], v[64:67], v[0:15]
	v_mfma_f32_32x32x16_bf16 v[48:63], v[176:179], v[68:71], v[48:63]
	v_mfma_f32_32x32x16_bf16 v[32:47], v[204:207], v[68:71], v[32:47]
	v_mfma_f32_32x32x16_bf16 v[16:31], v[192:195], v[68:71], v[16:31]
	v_mfma_f32_32x32x16_bf16 v[0:15], v[184:187], v[68:71], v[0:15]
	s_setprio 0
	s_setprio 1
	v_mfma_f32_32x32x16_bf16 v[64:79], v[168:171], v[80:83], v[238:253]
	ds_read_b128 v[180:183], v237 offset:53312
	v_mfma_f32_32x32x16_bf16 v[64:79], v[160:163], v[84:87], v[64:79]
	ds_read_b128 v[176:179], v237 offset:53344
	v_mfma_f32_32x32x16_bf16 v[64:79], v[164:167], v[88:91], v[64:79]
	ds_read_b128 v[184:187], v237 offset:57920
	v_mfma_f32_32x32x16_bf16 v[64:79], v[152:155], v[92:95], v[64:79]
	ds_read_b128 v[192:195], v237 offset:62528
	v_mfma_f32_32x32x16_bf16 v[64:79], v[156:159], v[96:99], v[64:79]
	ds_read_b128 v[196:199], v217 offset:13888
	v_mfma_f32_32x32x16_bf16 v[64:79], v[128:131], v[100:103], v[64:79]
	ds_read_b128 v[188:191], v217 offset:13920
	v_mfma_f32_32x32x16_bf16 v[64:79], v[132:135], v[104:107], v[64:79]
	ds_read_b128 v[200:203], v237 offset:57952
	v_mfma_f32_32x32x16_bf16 v[64:79], v[136:139], v[108:111], v[64:79]
	ds_read_b128 v[204:207], v237 offset:62560
	v_mfma_f32_32x32x16_bf16 v[64:79], v[140:143], v[112:115], v[64:79]
	v_mfma_f32_32x32x16_bf16 v[64:79], v[144:147], v[116:119], v[64:79]
	v_mfma_f32_32x32x16_bf16 v[64:79], v[148:151], v[120:123], v[64:79]
	v_mfma_f32_32x32x16_bf16 v[64:79], v[172:175], v[124:127], v[64:79]
	s_setprio 0
	s_waitcnt vmcnt(0) lgkmcnt(0)
	s_barrier
	s_add_i32 vcc_lo, s15, 63
	s_cmp_le_i32 vcc_lo, s86
	s_cbranch_scc1 .LBB0_1285
	v_add_u32_e32 v208, s15, v232
	v_add_u32_e32 v237, 32, v208
	v_cmp_lt_i32_e32 vcc, v237, v228
	s_nop 5
	v_cndmask_b32_e32 v65, v213, v65, vcc
	v_cmp_le_i32_e32 vcc, v237, v228
	v_add_u32_e32 v237, 34, v208
	s_nop 0
	v_cndmask_b32_e32 v64, v213, v64, vcc
	v_cmp_le_i32_e32 vcc, v237, v228
	v_add_u32_e32 v237, 35, v208
	s_nop 0
	v_cndmask_b32_e32 v66, v213, v66, vcc
	v_cmp_le_i32_e32 vcc, v237, v228
	v_add_u32_e32 v237, 40, v208
	s_nop 0
	v_cndmask_b32_e32 v67, v213, v67, vcc
	v_cmp_le_i32_e32 vcc, v237, v228
	v_add_u32_e32 v237, 41, v208
	s_nop 0
	v_cndmask_b32_e32 v68, v213, v68, vcc
	v_cmp_le_i32_e32 vcc, v237, v228
	v_add_u32_e32 v237, 42, v208
	s_nop 0
	v_cndmask_b32_e32 v69, v213, v69, vcc
	v_cmp_le_i32_e32 vcc, v237, v228
	v_add_u32_e32 v237, 43, v208
	s_nop 0
	v_cndmask_b32_e32 v70, v213, v70, vcc
	v_cmp_le_i32_e32 vcc, v237, v228
	v_add_u32_e32 v237, 48, v208
	s_nop 0
	v_cndmask_b32_e32 v71, v213, v71, vcc
	v_cmp_le_i32_e32 vcc, v237, v228
	v_add_u32_e32 v237, 49, v208
	s_nop 0
	v_cndmask_b32_e32 v72, v213, v72, vcc
	v_cmp_le_i32_e32 vcc, v237, v228
	v_add_u32_e32 v237, 50, v208
	s_nop 0
	v_cndmask_b32_e32 v73, v213, v73, vcc
	v_cmp_le_i32_e32 vcc, v237, v228
	v_add_u32_e32 v237, 51, v208
	s_nop 0
	v_cndmask_b32_e32 v74, v213, v74, vcc
	v_cmp_le_i32_e32 vcc, v237, v228
	v_add_u32_e32 v237, 56, v208
	s_nop 0
	v_cndmask_b32_e32 v75, v213, v75, vcc
	v_cmp_le_i32_e32 vcc, v237, v228
	v_add_u32_e32 v237, 57, v208
	s_nop 0
	v_cndmask_b32_e32 v76, v213, v76, vcc
	v_cmp_le_i32_e32 vcc, v237, v228
	v_add_u32_e32 v237, 58, v208
	v_add_u32_e32 v208, 59, v208
	v_cndmask_b32_e32 v77, v213, v77, vcc
	v_cmp_le_i32_e32 vcc, v237, v228
	s_nop 1
	v_cndmask_b32_e32 v78, v213, v78, vcc
	v_cmp_le_i32_e32 vcc, v208, v228
	s_nop 1
	v_cndmask_b32_e32 v79, v213, v79, vcc
.LBB0_1285:
	s_nop 5
	v_max_f32_e32 v211, v64, v65
	v_max3_f32 v211, v211, v66, v67
	v_max3_f32 v211, v211, v68, v69
	v_max3_f32 v211, v211, v70, v71
	v_max3_f32 v211, v211, v72, v73
	v_max3_f32 v211, v211, v74, v75
	v_max3_f32 v211, v211, v76, v77
	v_max3_f32 v211, v211, v78, v79
	v_mov_b32_e32 v208, v211
	s_nop 1
	v_permlane32_swap_b32_e32 v211, v208
	v_max_f32_e32 v211, v211, v208
	v_cmp_lt_f32_e32 vcc, 0x41000000, v211
	s_cbranch_vccz .LBB0_1287
	v_max_f32_e32 v211, 0, v211
	v_exp_f32_e64 v208, -v211
	v_add_f32_e32 v236, v236, v211
	s_nop 0
	v_pk_mul_f32 v[62:63], v[62:63], v[208:209] op_sel_hi:[1,0]
	v_pk_mul_f32 v[60:61], v[60:61], v[208:209] op_sel_hi:[1,0]
	v_pk_mul_f32 v[58:59], v[58:59], v[208:209] op_sel_hi:[1,0]
	v_pk_mul_f32 v[56:57], v[56:57], v[208:209] op_sel_hi:[1,0]
	v_pk_mul_f32 v[54:55], v[54:55], v[208:209] op_sel_hi:[1,0]
	v_pk_mul_f32 v[52:53], v[52:53], v[208:209] op_sel_hi:[1,0]
	v_pk_mul_f32 v[50:51], v[50:51], v[208:209] op_sel_hi:[1,0]
	v_pk_mul_f32 v[48:49], v[48:49], v[208:209] op_sel_hi:[1,0]
	v_pk_mul_f32 v[46:47], v[46:47], v[208:209] op_sel_hi:[1,0]
	v_pk_mul_f32 v[44:45], v[44:45], v[208:209] op_sel_hi:[1,0]
	v_pk_mul_f32 v[42:43], v[42:43], v[208:209] op_sel_hi:[1,0]
	v_pk_mul_f32 v[40:41], v[40:41], v[208:209] op_sel_hi:[1,0]
	v_pk_mul_f32 v[38:39], v[38:39], v[208:209] op_sel_hi:[1,0]
	v_pk_mul_f32 v[36:37], v[36:37], v[208:209] op_sel_hi:[1,0]
	v_pk_mul_f32 v[34:35], v[34:35], v[208:209] op_sel_hi:[1,0]
	v_pk_mul_f32 v[32:33], v[32:33], v[208:209] op_sel_hi:[1,0]
	v_pk_mul_f32 v[30:31], v[30:31], v[208:209] op_sel_hi:[1,0]
	v_pk_mul_f32 v[28:29], v[28:29], v[208:209] op_sel_hi:[1,0]
	v_pk_mul_f32 v[26:27], v[26:27], v[208:209] op_sel_hi:[1,0]
	v_pk_mul_f32 v[24:25], v[24:25], v[208:209] op_sel_hi:[1,0]
	v_pk_mul_f32 v[22:23], v[22:23], v[208:209] op_sel_hi:[1,0]
	v_pk_mul_f32 v[20:21], v[20:21], v[208:209] op_sel_hi:[1,0]
	v_pk_mul_f32 v[18:19], v[18:19], v[208:209] op_sel_hi:[1,0]
	v_pk_mul_f32 v[16:17], v[16:17], v[208:209] op_sel_hi:[1,0]
	v_pk_mul_f32 v[14:15], v[14:15], v[208:209] op_sel_hi:[1,0]
	v_pk_mul_f32 v[12:13], v[12:13], v[208:209] op_sel_hi:[1,0]
	v_pk_mul_f32 v[10:11], v[10:11], v[208:209] op_sel_hi:[1,0]
	v_pk_mul_f32 v[8:9], v[8:9], v[208:209] op_sel_hi:[1,0]
	v_pk_mul_f32 v[6:7], v[6:7], v[208:209] op_sel_hi:[1,0]
	v_pk_mul_f32 v[4:5], v[4:5], v[208:209] op_sel_hi:[1,0]
	v_pk_mul_f32 v[2:3], v[2:3], v[208:209] op_sel_hi:[1,0]
	v_pk_mul_f32 v[0:1], v[0:1], v[208:209] op_sel_hi:[1,0]
	v_mul_f32_e32 v235, v235, v208
	v_sub_f32_e32 v64, v64, v211
	v_sub_f32_e32 v65, v65, v211
	v_sub_f32_e32 v66, v66, v211
	v_sub_f32_e32 v67, v67, v211
	v_sub_f32_e32 v68, v68, v211
	v_sub_f32_e32 v69, v69, v211
	v_sub_f32_e32 v70, v70, v211
	v_sub_f32_e32 v71, v71, v211
	v_sub_f32_e32 v72, v72, v211
	v_sub_f32_e32 v73, v73, v211
	v_sub_f32_e32 v74, v74, v211
	v_sub_f32_e32 v75, v75, v211
	v_sub_f32_e32 v76, v76, v211
	v_sub_f32_e32 v77, v77, v211
	v_sub_f32_e32 v78, v78, v211
	v_sub_f32_e32 v79, v79, v211
	v_sub_f32_e32 v238, v238, v211
	v_sub_f32_e32 v239, v239, v211
	v_sub_f32_e32 v240, v240, v211
	v_sub_f32_e32 v241, v241, v211
	v_sub_f32_e32 v242, v242, v211
	v_sub_f32_e32 v243, v243, v211
	v_sub_f32_e32 v244, v244, v211
	v_sub_f32_e32 v245, v245, v211
	v_sub_f32_e32 v246, v246, v211
	v_sub_f32_e32 v247, v247, v211
	v_sub_f32_e32 v248, v248, v211
	v_sub_f32_e32 v249, v249, v211
	v_sub_f32_e32 v250, v250, v211
	v_sub_f32_e32 v251, v251, v211
	v_sub_f32_e32 v252, v252, v211
	v_sub_f32_e32 v253, v253, v211
.LBB0_1287:
	v_exp_f32_e32 v64, v64
	v_exp_f32_e32 v65, v65
	v_exp_f32_e32 v66, v66
	v_exp_f32_e32 v67, v67
	v_exp_f32_e32 v68, v68
	v_add_f32_e32 v208, v64, v65
	v_exp_f32_e32 v69, v69
	v_exp_f32_e32 v70, v70
	v_add_f32_e32 v208, v66, v208
	v_exp_f32_e32 v71, v71
	v_add_f32_e32 v208, v67, v208
	v_exp_f32_e32 v72, v72
	v_add_f32_e32 v208, v68, v208
	v_exp_f32_e32 v73, v73
	v_add_f32_e32 v208, v69, v208
	v_exp_f32_e32 v74, v74
	v_add_f32_e32 v208, v70, v208
	v_exp_f32_e32 v75, v75
	v_add_f32_e32 v208, v71, v208
	v_exp_f32_e32 v76, v76
	v_add_f32_e32 v208, v72, v208
	v_exp_f32_e32 v77, v77
	v_add_f32_e32 v208, v73, v208
	v_exp_f32_e32 v78, v78
	v_add_f32_e32 v208, v74, v208
	v_exp_f32_e32 v79, v79
	v_add_f32_e32 v208, v75, v208
	v_add_f32_e32 v208, v76, v208
	v_add_f32_e32 v208, v77, v208
	v_add_f32_e32 v208, v78, v208
	v_add_f32_e32 v208, v79, v208
	v_add_f32_e32 v235, v235, v208
	v_cvt_pk_bf16_f32 v64, v64, v65
	v_cvt_pk_bf16_f32 v65, v66, v67
	v_cvt_pk_bf16_f32 v66, v68, v69
	v_cvt_pk_bf16_f32 v67, v70, v71
	v_cvt_pk_bf16_f32 v68, v72, v73
	v_cvt_pk_bf16_f32 v69, v74, v75
	v_cvt_pk_bf16_f32 v70, v76, v77
	v_cvt_pk_bf16_f32 v71, v78, v79
	s_branch .LBB0_1289
